# GEMM units: the full vmcnt drain before each unit's K-loop removed (epilogue stores retire under the first K-loop segments; counted waits inside the loop stay valid because older operations complete f
# baseline (speedup 1.0000x reference)
; template <class Epi>
; __device__ __forceinline__ void gemm_phase(LAS unsigned char* lds, const Gemm g, const TabSched& S, const Epi& E) {
;     ...
;         const bool has_next = S.next(ui + 1, nxt);
;         const char* nA = has_next ? nxt.A : cA; const char* nB = has_next ? nxt.B : cB;
;         const int nt = cur.nt;
;         for (int t = 0; t < nt; t += 2) {
;             const bool last = (t == nt - 2);
;             const char* a1 = cA + (size_t)(t + 1) * kstep;
;             const char* a2 = last ? nA : cA + (size_t)(t + 2) * kstep; const char* b2 = last ? nB : cB + (size_t)(t + 2) * kstep;
;             const char* a3 = a2 + kstep; const char* b3 = b2 + kstep;
;     ...
; #pragma unroll
;         for (int a = 0; a < 2; ++a)
; #pragma unroll
;             for (int b = 0; b < 2; ++b)
; #pragma unroll
;                 for (int m = 0; m < 4; ++m)
; #pragma unroll
;                     for (int n = 0; n < 2; ++n) acc[a][b][m][n] = (f32x4){0.f, 0.f, 0.f, 0.f};
;         cur = nxt; cA = nA; cB = nB; ++ui;
.LBB0_415:
	s_cmp_lt_i32 s13, 1
	s_cbranch_scc1 .LBB0_425
	s_and_b64 s[42:43], s[44:45], exec
	s_cselect_b32 s19, s9, s27
	s_cselect_b32 s42, s8, s26
	s_cselect_b32 s43, s11, s41
	s_cselect_b32 s46, s10, s40
	s_add_i32 s47, s13, -2
	s_add_u32 s48, s40, 0x100
	s_addc_u32 s49, s41, 0
	s_add_u32 s26, s26, 0x80
	v_mov_b32_e32 v8, 0
	s_addc_u32 s27, s27, 0
	s_mov_b32 s40, 0
	v_mov_b32_e32 v9, v8
	v_mov_b32_e32 v10, v8
	v_mov_b32_e32 v11, v8
	v_mov_b32_e32 v12, v8
	v_mov_b32_e32 v13, v8
	v_mov_b32_e32 v14, v8
	v_mov_b32_e32 v15, v8
	v_mov_b32_e32 v16, v8
	v_mov_b32_e32 v17, v8
	v_mov_b32_e32 v18, v8
	v_mov_b32_e32 v19, v8
	v_mov_b32_e32 v20, v8
	v_mov_b32_e32 v21, v8
	v_mov_b32_e32 v22, v8
	v_mov_b32_e32 v23, v8
	v_mov_b32_e32 v24, v8
	v_mov_b32_e32 v25, v8
	v_mov_b32_e32 v26, v8
	v_mov_b32_e32 v27, v8
	v_mov_b32_e32 v28, v8
	v_mov_b32_e32 v29, v8
	v_mov_b32_e32 v30, v8
	v_mov_b32_e32 v31, v8
	v_mov_b32_e32 v32, v8
	v_mov_b32_e32 v33, v8
	v_mov_b32_e32 v34, v8
	v_mov_b32_e32 v35, v8
	v_mov_b32_e32 v36, v8
	v_mov_b32_e32 v37, v8
	v_mov_b32_e32 v38, v8
	v_mov_b32_e32 v39, v8
	v_mov_b32_e32 v40, v8
	v_mov_b32_e32 v41, v8
	v_mov_b32_e32 v42, v8
	v_mov_b32_e32 v43, v8
	v_mov_b32_e32 v44, v8
	v_mov_b32_e32 v45, v8
	v_mov_b32_e32 v46, v8
	v_mov_b32_e32 v47, v8
	v_mov_b32_e32 v48, v8
	v_mov_b32_e32 v49, v8
	v_mov_b32_e32 v50, v8
	v_mov_b32_e32 v51, v8
	v_mov_b32_e32 v52, v8
	v_mov_b32_e32 v53, v8
	v_mov_b32_e32 v54, v8
	v_mov_b32_e32 v55, v8
	v_mov_b32_e32 v56, v8
	v_mov_b32_e32 v57, v8
	v_mov_b32_e32 v58, v8
	v_mov_b32_e32 v59, v8
	v_mov_b32_e32 v60, v8
	v_mov_b32_e32 v61, v8
	v_mov_b32_e32 v62, v8
	v_mov_b32_e32 v63, v8
	v_mov_b32_e32 v64, v8
	v_mov_b32_e32 v65, v8
	v_mov_b32_e32 v66, v8
	v_mov_b32_e32 v67, v8
	v_mov_b32_e32 v68, v8
	v_mov_b32_e32 v69, v8
	v_mov_b32_e32 v70, v8
	v_mov_b32_e32 v71, v8
	v_mov_b32_e32 v72, v8
	v_mov_b32_e32 v73, v8
	v_mov_b32_e32 v74, v8
	v_mov_b32_e32 v75, v8
	v_mov_b32_e32 v76, v8
	v_mov_b32_e32 v77, v8
	v_mov_b32_e32 v78, v8
	v_mov_b32_e32 v79, v8
	v_mov_b32_e32 v80, v8
	v_mov_b32_e32 v81, v8
	v_mov_b32_e32 v82, v8
	v_mov_b32_e32 v83, v8
	v_mov_b32_e32 v84, v8
	v_mov_b32_e32 v85, v8
	v_mov_b32_e32 v86, v8
	v_mov_b32_e32 v87, v8
	v_mov_b32_e32 v88, v8
	v_mov_b32_e32 v89, v8
	v_mov_b32_e32 v90, v8
	v_mov_b32_e32 v91, v8
	v_mov_b32_e32 v92, v8
	v_mov_b32_e32 v93, v8
	v_mov_b32_e32 v94, v8
	v_mov_b32_e32 v95, v8
	v_mov_b32_e32 v96, v8
	v_mov_b32_e32 v97, v8
	v_mov_b32_e32 v98, v8
	v_mov_b32_e32 v99, v8
	v_mov_b32_e32 v100, v8
	v_mov_b32_e32 v101, v8
	v_mov_b32_e32 v102, v8
	v_mov_b32_e32 v103, v8
	v_mov_b32_e32 v104, v8
	v_mov_b32_e32 v105, v8
	v_mov_b32_e32 v106, v8
	v_mov_b32_e32 v107, v8
	v_mov_b32_e32 v108, v8
	v_mov_b32_e32 v109, v8
	v_mov_b32_e32 v110, v8
	v_mov_b32_e32 v111, v8
	v_mov_b32_e32 v112, v8
	v_mov_b32_e32 v113, v8
	v_mov_b32_e32 v114, v8
	v_mov_b32_e32 v115, v8
	v_mov_b32_e32 v116, v8
	v_mov_b32_e32 v117, v8
	v_mov_b32_e32 v118, v8
	v_mov_b32_e32 v119, v8
	v_mov_b32_e32 v120, v8
	v_mov_b32_e32 v121, v8
	v_mov_b32_e32 v122, v8
	v_mov_b32_e32 v123, v8
	v_mov_b32_e32 v124, v8
	v_mov_b32_e32 v125, v8
	v_mov_b32_e32 v126, v8
	v_mov_b32_e32 v127, v8
	v_mov_b32_e32 v128, v8
	v_mov_b32_e32 v129, v8
	v_mov_b32_e32 v130, v8
	v_mov_b32_e32 v131, v8
	v_mov_b32_e32 v132, v8
	v_mov_b32_e32 v133, v8
	v_mov_b32_e32 v134, v8
	v_mov_b32_e32 v135, v8
